# K loops without s_setprio flips + one static s_setprio 1 for waves 0..3 at kernel entry (first real run)
# baseline (speedup 1.0000x reference)
_Z14fwd_megakernel6Params:
	s_mov_b32 s92, s2
	v_readfirstlane_b32 s101, v0
	s_nop 3
	s_and_b32 s101, s101, 0x3ff
	s_lshr_b32 s101, s101, 6
	s_cmp_lt_u32 s101, 4
	s_cbranch_scc0 .Lprio_done
	s_setprio 1
